# mlstm_pre gate GEMV: gate weights fetched once per workgroup (one eighth per wave) and shared through a 32 KB LDS stash instead of eight identical global fetches
# baseline (speedup 1.0000x reference)
.LBB0_398:
	s_lshl_b32 s0, s5, 4
	s_and_b32 s8, s0, 0xfffff000
	s_lshl_b32 s0, s89, 4
	s_and_b32 s97, s89, 3
	s_and_b32 s9, s0, 0xfc0
	s_lshl_b32 s0, s97, 13
	v_lshl_add_u64 v[120:121], v[130:131], 0, s[0:1]
	s_mov_b64 s[14:15], 0x1000
	s_waitcnt lgkmcnt(1)
	v_add_co_u32_e32 v2, vcc, 0x1000, v120
	v_lshl_add_u64 v[0:1], v[120:121], 0, s[14:15]
	s_waitcnt lgkmcnt(0)
	v_addc_co_u32_e32 v3, vcc, 0, v121, vcc
	s_mov_b64 s[14:15], 0x1800
	v_readfirstlane_b32 s98, v130
	v_readfirstlane_b32 s99, v131
	v_readfirstlane_b32 s32, v221
	s_lshr_b32 s32, s32, 6
	v_lshlrev_b32_e32 v248, 5, v220
	s_lshr_b32 s14, s32, 1
	s_lshl_b32 s14, s14, 11
	s_and_b32 s15, s32, 1
	s_lshl_b32 s15, s15, 4
	s_add_i32 s14, s14, s15
	s_add_i32 s14, s14, s0
	v_add_u32_e32 v248, s14, v248
	v_lshlrev_b32_e32 v252, 4, v220
	v_add_u32_e32 v252, 0x11000, v252
	s_lshl_b32 s14, s32, 10
	v_add_u32_e32 v249, s14, v252
	global_load_dwordx4 v[52:55], v248, s[98:99]
	s_add_u32 s98, s98, 0x8000
	s_addc_u32 s99, s99, 0
	global_load_dwordx4 v[44:47], v248, s[98:99]
	s_add_u32 s98, s98, 0x8000
	s_addc_u32 s99, s99, 0
	global_load_dwordx4 v[36:39], v248, s[98:99]
	s_add_u32 s98, s98, 0x8000
	s_addc_u32 s99, s99, 0
	global_load_dwordx4 v[32:35], v248, s[98:99]
	s_waitcnt vmcnt(3)
	ds_write_b128 v249, v[52:55]
	s_waitcnt vmcnt(2)
	ds_write_b128 v249, v[44:47] offset:8192
	s_waitcnt vmcnt(1)
	ds_write_b128 v249, v[36:39] offset:16384
	s_waitcnt vmcnt(0)
	ds_write_b128 v249, v[32:35] offset:24576
	s_waitcnt lgkmcnt(0)
	s_barrier
	ds_read_b128 v[52:55], v252
	ds_read_b128 v[44:47], v252 offset:1024
	ds_read_b128 v[36:39], v252 offset:2048
	ds_read_b128 v[32:35], v252 offset:3072
	ds_read_b128 v[48:51], v252 offset:4096
	ds_read_b128 v[40:43], v252 offset:5120
	ds_read_b128 v[60:63], v252 offset:6144
	ds_read_b128 v[56:59], v252 offset:7168
	ds_read_b128 v[68:71], v252 offset:8192
	ds_read_b128 v[64:67], v252 offset:9216
	ds_read_b128 v[0:3], v252 offset:10240
	ds_read_b128 v[4:7], v252 offset:11264
	ds_read_b128 v[8:11], v252 offset:12288
	ds_read_b128 v[12:15], v252 offset:13312
	ds_read_b128 v[76:79], v252 offset:14336
	ds_read_b128 v[72:75], v252 offset:15360
	ds_read_b128 v[104:107], v252 offset:16384
	ds_read_b128 v[100:103], v252 offset:17408
	ds_read_b128 v[108:111], v252 offset:18432
	ds_read_b128 v[96:99], v252 offset:19456
	ds_read_b128 v[92:95], v252 offset:20480
	ds_read_b128 v[80:83], v252 offset:21504
	ds_read_b128 v[88:91], v252 offset:22528
	ds_read_b128 v[84:87], v252 offset:23552
	ds_read_b128 v[116:119], v252 offset:24576
	ds_read_b128 v[112:115], v252 offset:25600
	ds_read_b128 v[16:19], v252 offset:26624
	ds_read_b128 v[20:23], v252 offset:27648
	ds_read_b128 v[24:27], v252 offset:28672
	ds_read_b128 v[28:31], v252 offset:29696
	ds_read_b128 v[120:123], v252 offset:30720
	ds_read_b128 v[124:127], v252 offset:31744
	s_waitcnt lgkmcnt(0)
	v_cmp_lt_i32_e32 vcc, v213, v212
	v_readfirstlane_b32 s95, v221
	s_lshr_b32 s12, s95, 6
	v_cndmask_b32_e32 v128, v210, v213, vcc
	v_cmp_lt_i32_e32 vcc, v214, v212
	s_lshl_b32 s0, s12, 3
	s_or_b32 s8, s8, s9
	v_cndmask_b32_e32 v141, v210, v214, vcc
	v_cmp_lt_i32_e32 vcc, v215, v212
	s_lshl_b32 s12, s12, 7
	s_add_i32 s0, s8, s0
	v_cndmask_b32_e32 v142, v210, v215, vcc
	v_cmp_lt_i32_e32 vcc, v216, v212
	v_lshlrev_b32_e32 v224, 2, v142
	s_add_i32 s12, s12, 0
	v_cndmask_b32_e32 v142, v210, v216, vcc
	v_cmp_lt_i32_e32 vcc, v217, v212
	v_lshlrev_b32_e32 v225, 2, v142
	s_lshl_b64 s[8:9], s[0:1], 12
	v_cndmask_b32_e32 v142, v210, v217, vcc
	v_cmp_lt_i32_e32 vcc, v218, v212
	v_lshlrev_b32_e32 v226, 2, v142
	v_lshlrev_b32_e32 v128, 2, v128
	v_cndmask_b32_e32 v142, v210, v218, vcc
	v_lshlrev_b32_e32 v141, 2, v141
	v_lshlrev_b32_e32 v227, 2, v142
	v_mov_b32_e32 v143, v61
	v_mov_b32_e32 v145, v63
	v_mov_b32_e32 v147, v57
	v_mov_b32_e32 v149, v59
	v_mov_b32_e32 v199, v45
	v_mov_b32_e32 v201, v47
	v_mov_b32_e32 v203, v53
	v_mov_b32_e32 v205, v55
	s_add_i32 s12, s12, 0x10800
	v_mov_b32_e32 v202, v68
	v_pk_mov_b32 v[194:195], v[2:3], v[38:39] op_sel:[1,0]
	v_pk_mov_b32 v[186:187], v[10:11], v[50:51] op_sel:[1,0]
	v_mov_b32_e32 v142, v76
	v_mov_b32_e32 v144, v78
	v_mov_b32_e32 v146, v72
	v_mov_b32_e32 v148, v74
	v_pk_mov_b32 v[182:183], v[14:15], v[42:43] op_sel:[1,0]
	v_pk_mov_b32 v[184:185], v[12:13], v[40:41] op_sel:[1,0]
	v_pk_mov_b32 v[188:189], v[8:9], v[48:49] op_sel:[1,0]
	v_pk_mov_b32 v[190:191], v[6:7], v[34:35] op_sel:[1,0]
	v_mov_b32_e32 v178, v104
	v_mov_b32_e32 v174, v100
	v_mov_b32_e32 v176, v102
	v_mov_b32_e32 v180, v106
	v_pk_mov_b32 v[192:193], v[4:5], v[32:33] op_sel:[1,0]
	v_pk_mov_b32 v[196:197], v[0:1], v[36:37] op_sel:[1,0]
	v_mov_b32_e32 v198, v64
	v_mov_b32_e32 v200, v66
	v_mov_b32_e32 v204, v70
	v_pk_mov_b32 v[52:53], v[68:69], v[52:53] op_sel:[1,0]
	v_pk_mov_b32 v[54:55], v[70:71], v[54:55] op_sel:[1,0]
	v_pk_mov_b32 v[44:45], v[64:65], v[44:45] op_sel:[1,0]
	v_pk_mov_b32 v[46:47], v[66:67], v[46:47] op_sel:[1,0]
	v_mov_b32_e32 v151, v89
	v_mov_b32_e32 v153, v91
	v_mov_b32_e32 v155, v85
	v_mov_b32_e32 v157, v87
	v_mov_b32_e32 v1, v37
	v_mov_b32_e32 v3, v39
	v_mov_b32_e32 v5, v33
	v_mov_b32_e32 v7, v35
	v_mov_b32_e32 v9, v49
	v_mov_b32_e32 v11, v51
	v_mov_b32_e32 v13, v41
	v_mov_b32_e32 v15, v43
	v_pk_mov_b32 v[32:33], v[76:77], v[60:61] op_sel:[1,0]
	v_pk_mov_b32 v[34:35], v[78:79], v[62:63] op_sel:[1,0]
	v_pk_mov_b32 v[36:37], v[72:73], v[56:57] op_sel:[1,0]
	v_pk_mov_b32 v[38:39], v[74:75], v[58:59] op_sel:[1,0]
	v_mov_b32_e32 v179, v117
	v_pk_mov_b32 v[170:171], v[18:19], v[110:111] op_sel:[1,0]
	v_pk_mov_b32 v[162:163], v[26:27], v[94:95] op_sel:[1,0]
	v_mov_b32_e32 v150, v120
	v_mov_b32_e32 v152, v122
	v_mov_b32_e32 v154, v124
	v_mov_b32_e32 v156, v126
	v_pk_mov_b32 v[158:159], v[30:31], v[82:83] op_sel:[1,0]
	v_pk_mov_b32 v[160:161], v[28:29], v[80:81] op_sel:[1,0]
	v_pk_mov_b32 v[164:165], v[24:25], v[92:93] op_sel:[1,0]
	v_pk_mov_b32 v[166:167], v[22:23], v[98:99] op_sel:[1,0]
	v_pk_mov_b32 v[168:169], v[20:21], v[96:97] op_sel:[1,0]
	v_pk_mov_b32 v[172:173], v[16:17], v[108:109] op_sel:[1,0]
	v_mov_b32_e32 v175, v113
	v_mov_b32_e32 v177, v115
	v_mov_b32_e32 v181, v119
	v_pk_mov_b32 v[68:69], v[104:105], v[116:117] op_sel:[1,0]
	v_pk_mov_b32 v[70:71], v[106:107], v[118:119] op_sel:[1,0]
	v_pk_mov_b32 v[64:65], v[100:101], v[112:113] op_sel:[1,0]
	v_pk_mov_b32 v[66:67], v[102:103], v[114:115] op_sel:[1,0]
	v_mov_b32_e32 v17, v109
	v_mov_b32_e32 v19, v111
	v_mov_b32_e32 v21, v97
	v_mov_b32_e32 v23, v99
	v_mov_b32_e32 v25, v93
	v_mov_b32_e32 v27, v95
	v_mov_b32_e32 v29, v81
	v_mov_b32_e32 v31, v83
	v_pk_mov_b32 v[40:41], v[120:121], v[88:89] op_sel:[1,0]
	v_pk_mov_b32 v[42:43], v[122:123], v[90:91] op_sel:[1,0]
	v_pk_mov_b32 v[48:49], v[124:125], v[84:85] op_sel:[1,0]
	v_pk_mov_b32 v[50:51], v[126:127], v[86:87] op_sel:[1,0]
	v_lshl_add_u64 v[56:57], v[138:139], 0, s[8:9]
	s_mov_b64 s[24:25], 0
	v_lshl_add_u64 v[246:247], v[56:57], 0, s[24:25]
	s_nop 0
	v_add_co_u32_e32 v246, vcc, 0xb100000, v246
	s_nop 1
	v_addc_co_u32_e32 v247, vcc, 0, v247, vcc
	global_load_dwordx4 v[230:233], v[246:247], off
	global_load_dwordx4 v[234:237], v[246:247], off offset:1024
	global_load_dwordx4 v[238:241], v[246:247], off offset:2048
	global_load_dwordx4 v[242:245], v[246:247], off offset:3072
	s_branch .LBB0_400
